# down-proj tail consumer: streaming of each producer's slab starts right after that producer's flag (polls moved to slab boundaries) instead of after all three flags
# baseline (speedup 1.0000x reference)
; #define PG8_BAR __builtin_amdgcn_s_barrier()
; template <int KK, class Epi, class Sched, bool ALIGN_EPI = true>
; __device__ __forceinline__ void gemm_phase(LAS unsigned char* lds, const bf16* gA, const bf16* gBt, const Sched& S, const Epi& E, const int wid) {
;     ...
;         if constexpr (ALIGN_EPI) { if (wr == 0) PG8_BAR; }
;         E(acc, cur, wr, wc, fr, fq);
;         if (!has_next) break;
.Lp5a_poll2:
	global_load_dword v142, v141, s[44:45] offset:3208 sc1
	s_waitcnt vmcnt(0)
	v_readfirstlane_b32 s82, v142
	s_nop 0
	s_cmp_ge_u32 s82, 8
	s_cbranch_scc1 .Lp5a_go2
	s_sleep 1
	s_branch .Lp5a_poll2
.Lp5a_go2:
	s_add_u32 s78, s76, 0x40000
	s_addc_u32 s79, s77, 0
	global_load_dwordx4 v[200:203], v140, s[78:79] sc0 sc1
	s_add_u32 s78, s78, 0x2000
	s_addc_u32 s79, s79, 0
	global_load_dwordx4 v[204:207], v140, s[78:79] sc0 sc1
	s_add_u32 s78, s78, 0x2000
	s_addc_u32 s79, s79, 0
	global_load_dwordx4 v[208:211], v140, s[78:79] sc0 sc1
	s_add_u32 s78, s78, 0x2000
	s_addc_u32 s79, s79, 0
	global_load_dwordx4 v[212:215], v140, s[78:79] sc0 sc1
	s_add_u32 s78, s78, 0x2000
	s_addc_u32 s79, s79, 0
	global_load_dwordx4 v[216:219], v140, s[78:79] sc0 sc1
	s_add_u32 s78, s78, 0x2000
	s_addc_u32 s79, s79, 0
	global_load_dwordx4 v[220:223], v140, s[78:79] sc0 sc1
	s_add_u32 s78, s78, 0x2000
	s_addc_u32 s79, s79, 0
	global_load_dwordx4 v[224:227], v140, s[78:79] sc0 sc1
	s_add_u32 s78, s78, 0x2000
	s_addc_u32 s79, s79, 0
	global_load_dwordx4 v[228:231], v140, s[78:79] sc0 sc1
	s_add_u32 s78, s78, 0x2000
	s_addc_u32 s79, s79, 0
	global_load_dwordx4 v[232:235], v140, s[78:79] sc0 sc1
	s_add_u32 s78, s78, 0x2000
	s_addc_u32 s79, s79, 0
	global_load_dwordx4 v[236:239], v140, s[78:79] sc0 sc1
	s_add_u32 s78, s78, 0x2000
	s_addc_u32 s79, s79, 0
	global_load_dwordx4 v[240:243], v140, s[78:79] sc0 sc1
	s_add_u32 s78, s78, 0x2000
	s_addc_u32 s79, s79, 0
	global_load_dwordx4 v[244:247], v140, s[78:79] sc0 sc1
	s_add_u32 s78, s78, 0x2000
	s_addc_u32 s79, s79, 0
	global_load_dwordx4 v[160:163], v140, s[78:79] sc0 sc1
	s_add_u32 s78, s78, 0x2000
	s_addc_u32 s79, s79, 0
	global_load_dwordx4 v[164:167], v140, s[78:79] sc0 sc1
	s_add_u32 s78, s78, 0x2000
	s_addc_u32 s79, s79, 0
	global_load_dwordx4 v[168:171], v140, s[78:79] sc0 sc1
	s_add_u32 s78, s78, 0x2000
	s_addc_u32 s79, s79, 0
	global_load_dwordx4 v[172:175], v140, s[78:79] sc0 sc1
	s_waitcnt vmcnt(15)
	v_pk_add_f32 v[0:1], v[0:1], v[200:201]
	v_pk_add_f32 v[2:3], v[2:3], v[202:203]
	s_add_u32 s78, s78, 0x2000
	s_addc_u32 s79, s79, 0
	global_load_dwordx4 v[200:203], v140, s[78:79] sc0 sc1
	s_waitcnt vmcnt(15)
	v_pk_add_f32 v[4:5], v[4:5], v[204:205]
	v_pk_add_f32 v[6:7], v[6:7], v[206:207]
	s_add_u32 s78, s78, 0x2000
	s_addc_u32 s79, s79, 0
	global_load_dwordx4 v[204:207], v140, s[78:79] sc0 sc1
	s_waitcnt vmcnt(15)
	v_pk_add_f32 v[8:9], v[8:9], v[208:209]
	v_pk_add_f32 v[10:11], v[10:11], v[210:211]
	s_add_u32 s78, s78, 0x2000
	s_addc_u32 s79, s79, 0
	global_load_dwordx4 v[208:211], v140, s[78:79] sc0 sc1
	s_waitcnt vmcnt(15)
	v_pk_add_f32 v[12:13], v[12:13], v[212:213]
	v_pk_add_f32 v[14:15], v[14:15], v[214:215]
	s_add_u32 s78, s78, 0x2000
	s_addc_u32 s79, s79, 0
	global_load_dwordx4 v[212:215], v140, s[78:79] sc0 sc1
	s_waitcnt vmcnt(15)
	v_pk_add_f32 v[16:17], v[16:17], v[216:217]
	v_pk_add_f32 v[18:19], v[18:19], v[218:219]
	s_add_u32 s78, s78, 0x2000
	s_addc_u32 s79, s79, 0
	global_load_dwordx4 v[216:219], v140, s[78:79] sc0 sc1
	s_waitcnt vmcnt(15)
	v_pk_add_f32 v[20:21], v[20:21], v[220:221]
	v_pk_add_f32 v[22:23], v[22:23], v[222:223]
	s_add_u32 s78, s78, 0x2000
	s_addc_u32 s79, s79, 0
	global_load_dwordx4 v[220:223], v140, s[78:79] sc0 sc1
	s_waitcnt vmcnt(15)
	v_pk_add_f32 v[24:25], v[24:25], v[224:225]
	v_pk_add_f32 v[26:27], v[26:27], v[226:227]
	s_add_u32 s78, s78, 0x2000
	s_addc_u32 s79, s79, 0
	global_load_dwordx4 v[224:227], v140, s[78:79] sc0 sc1
	s_waitcnt vmcnt(15)
	v_pk_add_f32 v[28:29], v[28:29], v[228:229]
	v_pk_add_f32 v[30:31], v[30:31], v[230:231]
	s_add_u32 s78, s78, 0x2000
	s_addc_u32 s79, s79, 0
	global_load_dwordx4 v[228:231], v140, s[78:79] sc0 sc1
	s_waitcnt vmcnt(15)
	v_pk_add_f32 v[32:33], v[32:33], v[232:233]
	v_pk_add_f32 v[34:35], v[34:35], v[234:235]
	s_add_u32 s78, s78, 0x2000
	s_addc_u32 s79, s79, 0
	global_load_dwordx4 v[232:235], v140, s[78:79] sc0 sc1
	s_waitcnt vmcnt(15)
	v_pk_add_f32 v[36:37], v[36:37], v[236:237]
	v_pk_add_f32 v[38:39], v[38:39], v[238:239]
	s_add_u32 s78, s78, 0x2000
	s_addc_u32 s79, s79, 0
	global_load_dwordx4 v[236:239], v140, s[78:79] sc0 sc1
	s_waitcnt vmcnt(15)
	v_pk_add_f32 v[40:41], v[40:41], v[240:241]
	v_pk_add_f32 v[42:43], v[42:43], v[242:243]
	s_add_u32 s78, s78, 0x2000
	s_addc_u32 s79, s79, 0
	global_load_dwordx4 v[240:243], v140, s[78:79] sc0 sc1
	s_waitcnt vmcnt(15)
	v_pk_add_f32 v[44:45], v[44:45], v[244:245]
	v_pk_add_f32 v[46:47], v[46:47], v[246:247]
	s_add_u32 s78, s78, 0x2000
	s_addc_u32 s79, s79, 0
	global_load_dwordx4 v[244:247], v140, s[78:79] sc0 sc1
	s_waitcnt vmcnt(15)
	v_pk_add_f32 v[48:49], v[48:49], v[160:161]
	v_pk_add_f32 v[50:51], v[50:51], v[162:163]
	s_add_u32 s78, s78, 0x2000
	s_addc_u32 s79, s79, 0
	global_load_dwordx4 v[160:163], v140, s[78:79] sc0 sc1
	s_waitcnt vmcnt(15)
	v_pk_add_f32 v[52:53], v[52:53], v[164:165]
	v_pk_add_f32 v[54:55], v[54:55], v[166:167]
	s_add_u32 s78, s78, 0x2000
	s_addc_u32 s79, s79, 0
	global_load_dwordx4 v[164:167], v140, s[78:79] sc0 sc1
	s_waitcnt vmcnt(15)
	v_pk_add_f32 v[56:57], v[56:57], v[168:169]
	v_pk_add_f32 v[58:59], v[58:59], v[170:171]
	s_add_u32 s78, s78, 0x2000
	s_addc_u32 s79, s79, 0
	global_load_dwordx4 v[168:171], v140, s[78:79] sc0 sc1
	s_waitcnt vmcnt(15)
	v_pk_add_f32 v[60:61], v[60:61], v[172:173]
	v_pk_add_f32 v[62:63], v[62:63], v[174:175]
	s_add_u32 s78, s78, 0x2000
	s_addc_u32 s79, s79, 0
	global_load_dwordx4 v[172:175], v140, s[78:79] sc0 sc1
	s_waitcnt vmcnt(15)
	v_pk_add_f32 v[64:65], v[64:65], v[200:201]
	v_pk_add_f32 v[66:67], v[66:67], v[202:203]
; #define PG8_BAR __builtin_amdgcn_s_barrier()
; template <int KK, class Epi, class Sched, bool ALIGN_EPI = true>
; __device__ __forceinline__ void gemm_phase(LAS unsigned char* lds, const bf16* gA, const bf16* gBt, const Sched& S, const Epi& E, const int wid) {
;     ...
;         if constexpr (ALIGN_EPI) { if (wr == 0) PG8_BAR; }
;         E(acc, cur, wr, wc, fr, fq);
;         if (!has_next) break;
.Lp5a_poll3:
	global_load_dword v142, v141, s[44:45] offset:3212 sc1
	s_waitcnt vmcnt(0)
	v_readfirstlane_b32 s82, v142
	s_nop 0
	s_cmp_ge_u32 s82, 8
	s_cbranch_scc1 .Lp5a_go3
	s_sleep 1
	s_branch .Lp5a_poll3
.Lp5a_go3:
	s_add_u32 s78, s76, 0x80000
	s_addc_u32 s79, s77, 0
	global_load_dwordx4 v[200:203], v140, s[78:79] sc0 sc1
	s_waitcnt vmcnt(15)
	v_pk_add_f32 v[68:69], v[68:69], v[204:205]
	v_pk_add_f32 v[70:71], v[70:71], v[206:207]
	s_add_u32 s78, s78, 0x2000
	s_addc_u32 s79, s79, 0
	global_load_dwordx4 v[204:207], v140, s[78:79] sc0 sc1
	s_waitcnt vmcnt(15)
	v_pk_add_f32 v[72:73], v[72:73], v[208:209]
	v_pk_add_f32 v[74:75], v[74:75], v[210:211]
	s_add_u32 s78, s78, 0x2000
	s_addc_u32 s79, s79, 0
	global_load_dwordx4 v[208:211], v140, s[78:79] sc0 sc1
	s_waitcnt vmcnt(15)
	v_pk_add_f32 v[76:77], v[76:77], v[212:213]
	v_pk_add_f32 v[78:79], v[78:79], v[214:215]
	s_add_u32 s78, s78, 0x2000
	s_addc_u32 s79, s79, 0
	global_load_dwordx4 v[212:215], v140, s[78:79] sc0 sc1
	s_waitcnt vmcnt(15)
	v_pk_add_f32 v[80:81], v[80:81], v[216:217]
	v_pk_add_f32 v[82:83], v[82:83], v[218:219]
	s_add_u32 s78, s78, 0x2000
	s_addc_u32 s79, s79, 0
	global_load_dwordx4 v[216:219], v140, s[78:79] sc0 sc1
	s_waitcnt vmcnt(15)
	v_pk_add_f32 v[84:85], v[84:85], v[220:221]
	v_pk_add_f32 v[86:87], v[86:87], v[222:223]
	s_add_u32 s78, s78, 0x2000
	s_addc_u32 s79, s79, 0
	global_load_dwordx4 v[220:223], v140, s[78:79] sc0 sc1
	s_waitcnt vmcnt(15)
	v_pk_add_f32 v[88:89], v[88:89], v[224:225]
	v_pk_add_f32 v[90:91], v[90:91], v[226:227]
	s_add_u32 s78, s78, 0x2000
	s_addc_u32 s79, s79, 0
	global_load_dwordx4 v[224:227], v140, s[78:79] sc0 sc1
	s_waitcnt vmcnt(15)
	v_pk_add_f32 v[92:93], v[92:93], v[228:229]
	v_pk_add_f32 v[94:95], v[94:95], v[230:231]
	s_add_u32 s78, s78, 0x2000
	s_addc_u32 s79, s79, 0
	global_load_dwordx4 v[228:231], v140, s[78:79] sc0 sc1
	s_waitcnt vmcnt(15)
	v_pk_add_f32 v[96:97], v[96:97], v[232:233]
	v_pk_add_f32 v[98:99], v[98:99], v[234:235]
	s_add_u32 s78, s78, 0x2000
	s_addc_u32 s79, s79, 0
	global_load_dwordx4 v[232:235], v140, s[78:79] sc0 sc1
	s_waitcnt vmcnt(15)
	v_pk_add_f32 v[100:101], v[100:101], v[236:237]
	v_pk_add_f32 v[102:103], v[102:103], v[238:239]
	s_add_u32 s78, s78, 0x2000
	s_addc_u32 s79, s79, 0
	global_load_dwordx4 v[236:239], v140, s[78:79] sc0 sc1
	s_waitcnt vmcnt(15)
	v_pk_add_f32 v[104:105], v[104:105], v[240:241]
	v_pk_add_f32 v[106:107], v[106:107], v[242:243]
	s_add_u32 s78, s78, 0x2000
	s_addc_u32 s79, s79, 0
	global_load_dwordx4 v[240:243], v140, s[78:79] sc0 sc1
	s_waitcnt vmcnt(15)
	v_pk_add_f32 v[108:109], v[108:109], v[244:245]
	v_pk_add_f32 v[110:111], v[110:111], v[246:247]
	s_add_u32 s78, s78, 0x2000
	s_addc_u32 s79, s79, 0
	global_load_dwordx4 v[244:247], v140, s[78:79] sc0 sc1
	s_waitcnt vmcnt(15)
	v_pk_add_f32 v[112:113], v[112:113], v[160:161]
	v_pk_add_f32 v[114:115], v[114:115], v[162:163]
	s_add_u32 s78, s78, 0x2000
	s_addc_u32 s79, s79, 0
	global_load_dwordx4 v[160:163], v140, s[78:79] sc0 sc1
	s_waitcnt vmcnt(15)
	v_pk_add_f32 v[116:117], v[116:117], v[164:165]
	v_pk_add_f32 v[118:119], v[118:119], v[166:167]
	s_add_u32 s78, s78, 0x2000
	s_addc_u32 s79, s79, 0
	global_load_dwordx4 v[164:167], v140, s[78:79] sc0 sc1
	s_waitcnt vmcnt(15)
	v_pk_add_f32 v[120:121], v[120:121], v[168:169]
	v_pk_add_f32 v[122:123], v[122:123], v[170:171]
	s_add_u32 s78, s78, 0x2000
	s_addc_u32 s79, s79, 0
	global_load_dwordx4 v[168:171], v140, s[78:79] sc0 sc1
	s_waitcnt vmcnt(15)
	v_pk_add_f32 v[124:125], v[124:125], v[172:173]
	v_pk_add_f32 v[126:127], v[126:127], v[174:175]
	s_add_u32 s78, s78, 0x2000
	s_addc_u32 s79, s79, 0
	global_load_dwordx4 v[172:175], v140, s[78:79] sc0 sc1
	s_waitcnt vmcnt(15)
; #define PG8_BAR __builtin_amdgcn_s_barrier()
; template <int KK, class Epi, class Sched, bool ALIGN_EPI = true>
; __device__ __forceinline__ void gemm_phase(LAS unsigned char* lds, const bf16* gA, const bf16* gBt, const Sched& S, const Epi& E, const int wid) {
;     ...
;         if constexpr (ALIGN_EPI) { if (wr == 0) PG8_BAR; }
;         E(acc, cur, wr, wc, fr, fq);
;         if (!has_next) break;
	v_pk_add_f32 v[0:1], v[0:1], v[200:201]
	v_pk_add_f32 v[2:3], v[2:3], v[202:203]
	s_add_u32 s78, s78, 0x2000
	s_addc_u32 s79, s79, 0
	global_load_dwordx4 v[200:203], v140, s[78:79] sc0 sc1
	s_waitcnt vmcnt(15)
	v_pk_add_f32 v[4:5], v[4:5], v[204:205]
	v_pk_add_f32 v[6:7], v[6:7], v[206:207]
	s_add_u32 s78, s78, 0x2000
	s_addc_u32 s79, s79, 0
	global_load_dwordx4 v[204:207], v140, s[78:79] sc0 sc1
	s_waitcnt vmcnt(15)
	v_pk_add_f32 v[8:9], v[8:9], v[208:209]
	v_pk_add_f32 v[10:11], v[10:11], v[210:211]
	s_add_u32 s78, s78, 0x2000
	s_addc_u32 s79, s79, 0
	global_load_dwordx4 v[208:211], v140, s[78:79] sc0 sc1
	s_waitcnt vmcnt(15)
	v_pk_add_f32 v[12:13], v[12:13], v[212:213]
	v_pk_add_f32 v[14:15], v[14:15], v[214:215]
	s_add_u32 s78, s78, 0x2000
	s_addc_u32 s79, s79, 0
	global_load_dwordx4 v[212:215], v140, s[78:79] sc0 sc1
	s_waitcnt vmcnt(15)
	v_pk_add_f32 v[16:17], v[16:17], v[216:217]
	v_pk_add_f32 v[18:19], v[18:19], v[218:219]
	s_add_u32 s78, s78, 0x2000
	s_addc_u32 s79, s79, 0
	global_load_dwordx4 v[216:219], v140, s[78:79] sc0 sc1
	s_waitcnt vmcnt(15)
	v_pk_add_f32 v[20:21], v[20:21], v[220:221]
	v_pk_add_f32 v[22:23], v[22:23], v[222:223]
	s_add_u32 s78, s78, 0x2000
	s_addc_u32 s79, s79, 0
	global_load_dwordx4 v[220:223], v140, s[78:79] sc0 sc1
	s_waitcnt vmcnt(15)
	v_pk_add_f32 v[24:25], v[24:25], v[224:225]
	v_pk_add_f32 v[26:27], v[26:27], v[226:227]
	s_add_u32 s78, s78, 0x2000
	s_addc_u32 s79, s79, 0
	global_load_dwordx4 v[224:227], v140, s[78:79] sc0 sc1
	s_waitcnt vmcnt(15)
	v_pk_add_f32 v[28:29], v[28:29], v[228:229]
	v_pk_add_f32 v[30:31], v[30:31], v[230:231]
	s_add_u32 s78, s78, 0x2000
	s_addc_u32 s79, s79, 0
	global_load_dwordx4 v[228:231], v140, s[78:79] sc0 sc1
	s_waitcnt vmcnt(15)
	v_pk_add_f32 v[32:33], v[32:33], v[232:233]
	v_pk_add_f32 v[34:35], v[34:35], v[234:235]
	s_add_u32 s78, s78, 0x2000
	s_addc_u32 s79, s79, 0
	global_load_dwordx4 v[232:235], v140, s[78:79] sc0 sc1
	s_waitcnt vmcnt(15)
	v_pk_add_f32 v[36:37], v[36:37], v[236:237]
	v_pk_add_f32 v[38:39], v[38:39], v[238:239]
	s_add_u32 s78, s78, 0x2000
	s_addc_u32 s79, s79, 0
	global_load_dwordx4 v[236:239], v140, s[78:79] sc0 sc1
	s_waitcnt vmcnt(15)
	v_pk_add_f32 v[40:41], v[40:41], v[240:241]
	v_pk_add_f32 v[42:43], v[42:43], v[242:243]
	s_add_u32 s78, s78, 0x2000
	s_addc_u32 s79, s79, 0
	global_load_dwordx4 v[240:243], v140, s[78:79] sc0 sc1
	s_waitcnt vmcnt(15)
	v_pk_add_f32 v[44:45], v[44:45], v[244:245]
	v_pk_add_f32 v[46:47], v[46:47], v[246:247]
	s_add_u32 s78, s78, 0x2000
	s_addc_u32 s79, s79, 0
	global_load_dwordx4 v[244:247], v140, s[78:79] sc0 sc1
	s_waitcnt vmcnt(15)
	v_pk_add_f32 v[48:49], v[48:49], v[160:161]
	v_pk_add_f32 v[50:51], v[50:51], v[162:163]
	s_add_u32 s78, s78, 0x2000
	s_addc_u32 s79, s79, 0
	global_load_dwordx4 v[160:163], v140, s[78:79] sc0 sc1
	s_waitcnt vmcnt(15)
	v_pk_add_f32 v[52:53], v[52:53], v[164:165]
	v_pk_add_f32 v[54:55], v[54:55], v[166:167]
	s_add_u32 s78, s78, 0x2000
	s_addc_u32 s79, s79, 0
	global_load_dwordx4 v[164:167], v140, s[78:79] sc0 sc1
	s_waitcnt vmcnt(15)
	v_pk_add_f32 v[56:57], v[56:57], v[168:169]
	v_pk_add_f32 v[58:59], v[58:59], v[170:171]
	s_add_u32 s78, s78, 0x2000
	s_addc_u32 s79, s79, 0
	global_load_dwordx4 v[168:171], v140, s[78:79] sc0 sc1
	s_waitcnt vmcnt(15)
	v_pk_add_f32 v[60:61], v[60:61], v[172:173]
	v_pk_add_f32 v[62:63], v[62:63], v[174:175]
	s_add_u32 s78, s78, 0x2000
	s_addc_u32 s79, s79, 0
	global_load_dwordx4 v[172:175], v140, s[78:79] sc0 sc1
	s_waitcnt vmcnt(15)
	v_pk_add_f32 v[64:65], v[64:65], v[200:201]
	v_pk_add_f32 v[66:67], v[66:67], v[202:203]

; #define PG8_BAR __builtin_amdgcn_s_barrier()
; template <int KK, class Epi, class Sched, bool ALIGN_EPI = true>
; __device__ __forceinline__ void gemm_phase(LAS unsigned char* lds, const bf16* gA, const bf16* gBt, const Sched& S, const Epi& E, const int wid) {
;     ...
;         if constexpr (ALIGN_EPI) { if (wr == 0) PG8_BAR; }
;         E(acc, cur, wr, wc, fr, fq);
;         if (!has_next) break;
.Lp5a_go1:
	s_add_u32 s78, s76, 0x0
	s_addc_u32 s79, s77, 0
	global_load_dwordx4 v[200:203], v140, s[78:79] sc0 sc1
	s_waitcnt vmcnt(15)
	v_pk_add_f32 v[68:69], v[68:69], v[204:205]
	v_pk_add_f32 v[70:71], v[70:71], v[206:207]
	s_add_u32 s78, s78, 0x2000
	s_addc_u32 s79, s79, 0
	global_load_dwordx4 v[204:207], v140, s[78:79] sc0 sc1
	s_waitcnt vmcnt(15)
	v_pk_add_f32 v[72:73], v[72:73], v[208:209]
	v_pk_add_f32 v[74:75], v[74:75], v[210:211]
	s_add_u32 s78, s78, 0x2000
	s_addc_u32 s79, s79, 0
	global_load_dwordx4 v[208:211], v140, s[78:79] sc0 sc1
	s_waitcnt vmcnt(15)
	v_pk_add_f32 v[76:77], v[76:77], v[212:213]
	v_pk_add_f32 v[78:79], v[78:79], v[214:215]
	s_add_u32 s78, s78, 0x2000
	s_addc_u32 s79, s79, 0
	global_load_dwordx4 v[212:215], v140, s[78:79] sc0 sc1
	s_waitcnt vmcnt(15)
	v_pk_add_f32 v[80:81], v[80:81], v[216:217]
	v_pk_add_f32 v[82:83], v[82:83], v[218:219]
	s_add_u32 s78, s78, 0x2000
	s_addc_u32 s79, s79, 0
	global_load_dwordx4 v[216:219], v140, s[78:79] sc0 sc1
	s_waitcnt vmcnt(15)
	v_pk_add_f32 v[84:85], v[84:85], v[220:221]
	v_pk_add_f32 v[86:87], v[86:87], v[222:223]
	s_add_u32 s78, s78, 0x2000
	s_addc_u32 s79, s79, 0
	global_load_dwordx4 v[220:223], v140, s[78:79] sc0 sc1
	s_waitcnt vmcnt(15)
	v_pk_add_f32 v[88:89], v[88:89], v[224:225]
	v_pk_add_f32 v[90:91], v[90:91], v[226:227]
	s_add_u32 s78, s78, 0x2000
	s_addc_u32 s79, s79, 0
	global_load_dwordx4 v[224:227], v140, s[78:79] sc0 sc1
	s_waitcnt vmcnt(15)
	v_pk_add_f32 v[92:93], v[92:93], v[228:229]
	v_pk_add_f32 v[94:95], v[94:95], v[230:231]
	s_add_u32 s78, s78, 0x2000
	s_addc_u32 s79, s79, 0
	global_load_dwordx4 v[228:231], v140, s[78:79] sc0 sc1
	s_waitcnt vmcnt(15)
	v_pk_add_f32 v[96:97], v[96:97], v[232:233]
	v_pk_add_f32 v[98:99], v[98:99], v[234:235]
	s_add_u32 s78, s78, 0x2000
	s_addc_u32 s79, s79, 0
	global_load_dwordx4 v[232:235], v140, s[78:79] sc0 sc1
	s_waitcnt vmcnt(15)
	v_pk_add_f32 v[100:101], v[100:101], v[236:237]
	v_pk_add_f32 v[102:103], v[102:103], v[238:239]
	s_add_u32 s78, s78, 0x2000
	s_addc_u32 s79, s79, 0
	global_load_dwordx4 v[236:239], v140, s[78:79] sc0 sc1
	s_waitcnt vmcnt(15)
	v_pk_add_f32 v[104:105], v[104:105], v[240:241]
	v_pk_add_f32 v[106:107], v[106:107], v[242:243]
	s_add_u32 s78, s78, 0x2000
	s_addc_u32 s79, s79, 0
	global_load_dwordx4 v[240:243], v140, s[78:79] sc0 sc1
	s_waitcnt vmcnt(15)
	v_pk_add_f32 v[108:109], v[108:109], v[244:245]
	v_pk_add_f32 v[110:111], v[110:111], v[246:247]
	s_add_u32 s78, s78, 0x2000
	s_addc_u32 s79, s79, 0
	global_load_dwordx4 v[244:247], v140, s[78:79] sc0 sc1
	s_waitcnt vmcnt(15)
	v_pk_add_f32 v[112:113], v[112:113], v[160:161]
	v_pk_add_f32 v[114:115], v[114:115], v[162:163]
	s_add_u32 s78, s78, 0x2000
	s_addc_u32 s79, s79, 0
	global_load_dwordx4 v[160:163], v140, s[78:79] sc0 sc1
	s_waitcnt vmcnt(15)
	v_pk_add_f32 v[116:117], v[116:117], v[164:165]
	v_pk_add_f32 v[118:119], v[118:119], v[166:167]
	s_add_u32 s78, s78, 0x2000
	s_addc_u32 s79, s79, 0
	global_load_dwordx4 v[164:167], v140, s[78:79] sc0 sc1
	s_waitcnt vmcnt(15)
	v_pk_add_f32 v[120:121], v[120:121], v[168:169]
	v_pk_add_f32 v[122:123], v[122:123], v[170:171]
	s_add_u32 s78, s78, 0x2000
	s_addc_u32 s79, s79, 0
	global_load_dwordx4 v[168:171], v140, s[78:79] sc0 sc1
	s_waitcnt vmcnt(15)
	v_pk_add_f32 v[124:125], v[124:125], v[172:173]
	v_pk_add_f32 v[126:127], v[126:127], v[174:175]
	s_add_u32 s78, s78, 0x2000
	s_addc_u32 s79, s79, 0
	global_load_dwordx4 v[172:175], v140, s[78:79] sc0 sc1
	s_waitcnt vmcnt(15)
	v_pk_add_f32 v[0:1], v[0:1], v[200:201]
	v_pk_add_f32 v[2:3], v[2:3], v[202:203]
	s_add_u32 s78, s78, 0x2000
	s_addc_u32 s79, s79, 0
	global_load_dwordx4 v[200:203], v140, s[78:79] sc0 sc1
	s_waitcnt vmcnt(15)
	v_pk_add_f32 v[4:5], v[4:5], v[204:205]
	v_pk_add_f32 v[6:7], v[6:7], v[206:207]
	s_add_u32 s78, s78, 0x2000
	s_addc_u32 s79, s79, 0
	global_load_dwordx4 v[204:207], v140, s[78:79] sc0 sc1
	s_waitcnt vmcnt(15)
	v_pk_add_f32 v[8:9], v[8:9], v[208:209]
	v_pk_add_f32 v[10:11], v[10:11], v[210:211]
	s_add_u32 s78, s78, 0x2000
	s_addc_u32 s79, s79, 0
	global_load_dwordx4 v[208:211], v140, s[78:79] sc0 sc1
	s_waitcnt vmcnt(15)
	v_pk_add_f32 v[12:13], v[12:13], v[212:213]
	v_pk_add_f32 v[14:15], v[14:15], v[214:215]
	s_add_u32 s78, s78, 0x2000
	s_addc_u32 s79, s79, 0
	global_load_dwordx4 v[212:215], v140, s[78:79] sc0 sc1
	s_waitcnt vmcnt(15)
; #define PG8_BAR __builtin_amdgcn_s_barrier()
; template <int KK, class Epi, class Sched, bool ALIGN_EPI = true>
; __device__ __forceinline__ void gemm_phase(LAS unsigned char* lds, const bf16* gA, const bf16* gBt, const Sched& S, const Epi& E, const int wid) {
;     ...
;         if constexpr (ALIGN_EPI) { if (wr == 0) PG8_BAR; }
;         E(acc, cur, wr, wc, fr, fq);
;         if (!has_next) break;
	v_pk_add_f32 v[16:17], v[16:17], v[216:217]
	v_pk_add_f32 v[18:19], v[18:19], v[218:219]
	s_add_u32 s78, s78, 0x2000
	s_addc_u32 s79, s79, 0
	global_load_dwordx4 v[216:219], v140, s[78:79] sc0 sc1
	s_waitcnt vmcnt(15)
	v_pk_add_f32 v[20:21], v[20:21], v[220:221]
	v_pk_add_f32 v[22:23], v[22:23], v[222:223]
	s_add_u32 s78, s78, 0x2000
	s_addc_u32 s79, s79, 0
	global_load_dwordx4 v[220:223], v140, s[78:79] sc0 sc1
	s_waitcnt vmcnt(15)
	v_pk_add_f32 v[24:25], v[24:25], v[224:225]
	v_pk_add_f32 v[26:27], v[26:27], v[226:227]
	s_add_u32 s78, s78, 0x2000
	s_addc_u32 s79, s79, 0
	global_load_dwordx4 v[224:227], v140, s[78:79] sc0 sc1
	s_waitcnt vmcnt(15)
	v_pk_add_f32 v[28:29], v[28:29], v[228:229]
	v_pk_add_f32 v[30:31], v[30:31], v[230:231]
	s_add_u32 s78, s78, 0x2000
	s_addc_u32 s79, s79, 0
	global_load_dwordx4 v[228:231], v140, s[78:79] sc0 sc1
	s_waitcnt vmcnt(15)
	v_pk_add_f32 v[32:33], v[32:33], v[232:233]
	v_pk_add_f32 v[34:35], v[34:35], v[234:235]
	s_add_u32 s78, s78, 0x2000
	s_addc_u32 s79, s79, 0
	global_load_dwordx4 v[232:235], v140, s[78:79] sc0 sc1
	s_waitcnt vmcnt(15)
	v_pk_add_f32 v[36:37], v[36:37], v[236:237]
	v_pk_add_f32 v[38:39], v[38:39], v[238:239]
	s_add_u32 s78, s78, 0x2000
	s_addc_u32 s79, s79, 0
	global_load_dwordx4 v[236:239], v140, s[78:79] sc0 sc1
	s_waitcnt vmcnt(15)
	v_pk_add_f32 v[40:41], v[40:41], v[240:241]
	v_pk_add_f32 v[42:43], v[42:43], v[242:243]
	s_add_u32 s78, s78, 0x2000
	s_addc_u32 s79, s79, 0
	global_load_dwordx4 v[240:243], v140, s[78:79] sc0 sc1
	s_waitcnt vmcnt(15)
	v_pk_add_f32 v[44:45], v[44:45], v[244:245]
	v_pk_add_f32 v[46:47], v[46:47], v[246:247]
	s_add_u32 s78, s78, 0x2000
	s_addc_u32 s79, s79, 0
	global_load_dwordx4 v[244:247], v140, s[78:79] sc0 sc1
	s_waitcnt vmcnt(15)
	v_pk_add_f32 v[48:49], v[48:49], v[160:161]
	v_pk_add_f32 v[50:51], v[50:51], v[162:163]
	s_add_u32 s78, s78, 0x2000
	s_addc_u32 s79, s79, 0
	global_load_dwordx4 v[160:163], v140, s[78:79] sc0 sc1
	s_waitcnt vmcnt(15)
	v_pk_add_f32 v[52:53], v[52:53], v[164:165]
	v_pk_add_f32 v[54:55], v[54:55], v[166:167]
	s_add_u32 s78, s78, 0x2000
	s_addc_u32 s79, s79, 0
	global_load_dwordx4 v[164:167], v140, s[78:79] sc0 sc1
	s_waitcnt vmcnt(15)
	v_pk_add_f32 v[56:57], v[56:57], v[168:169]
	v_pk_add_f32 v[58:59], v[58:59], v[170:171]
	s_add_u32 s78, s78, 0x2000
	s_addc_u32 s79, s79, 0
	global_load_dwordx4 v[168:171], v140, s[78:79] sc0 sc1
	s_waitcnt vmcnt(15)
	v_pk_add_f32 v[60:61], v[60:61], v[172:173]
	v_pk_add_f32 v[62:63], v[62:63], v[174:175]
	s_add_u32 s78, s78, 0x2000
	s_addc_u32 s79, s79, 0
	global_load_dwordx4 v[172:175], v140, s[78:79] sc0 sc1
	s_waitcnt vmcnt(15)
	v_pk_add_f32 v[64:65], v[64:65], v[200:201]
	v_pk_add_f32 v[66:67], v[66:67], v[202:203]
	s_waitcnt vmcnt(14)
	v_pk_add_f32 v[68:69], v[68:69], v[204:205]
	v_pk_add_f32 v[70:71], v[70:71], v[206:207]
	s_waitcnt vmcnt(13)
	v_pk_add_f32 v[72:73], v[72:73], v[208:209]
	v_pk_add_f32 v[74:75], v[74:75], v[210:211]
	s_waitcnt vmcnt(12)
	v_pk_add_f32 v[76:77], v[76:77], v[212:213]
	v_pk_add_f32 v[78:79], v[78:79], v[214:215]
	s_waitcnt vmcnt(11)
	v_pk_add_f32 v[80:81], v[80:81], v[216:217]
	v_pk_add_f32 v[82:83], v[82:83], v[218:219]
	s_waitcnt vmcnt(10)
	v_pk_add_f32 v[84:85], v[84:85], v[220:221]
	v_pk_add_f32 v[86:87], v[86:87], v[222:223]
	s_waitcnt vmcnt(9)
	v_pk_add_f32 v[88:89], v[88:89], v[224:225]
	v_pk_add_f32 v[90:91], v[90:91], v[226:227]
	s_waitcnt vmcnt(8)
	v_pk_add_f32 v[92:93], v[92:93], v[228:229]
	v_pk_add_f32 v[94:95], v[94:95], v[230:231]
	s_waitcnt vmcnt(7)
	v_pk_add_f32 v[96:97], v[96:97], v[232:233]
	v_pk_add_f32 v[98:99], v[98:99], v[234:235]
	s_waitcnt vmcnt(6)
	v_pk_add_f32 v[100:101], v[100:101], v[236:237]
	v_pk_add_f32 v[102:103], v[102:103], v[238:239]
	s_waitcnt vmcnt(5)
	v_pk_add_f32 v[104:105], v[104:105], v[240:241]
	v_pk_add_f32 v[106:107], v[106:107], v[242:243]
	s_waitcnt vmcnt(4)
	v_pk_add_f32 v[108:109], v[108:109], v[244:245]
	v_pk_add_f32 v[110:111], v[110:111], v[246:247]
	s_waitcnt vmcnt(3)
	v_pk_add_f32 v[112:113], v[112:113], v[160:161]
	v_pk_add_f32 v[114:115], v[114:115], v[162:163]
	s_waitcnt vmcnt(2)
	v_pk_add_f32 v[116:117], v[116:117], v[164:165]
	v_pk_add_f32 v[118:119], v[118:119], v[166:167]
	s_waitcnt vmcnt(1)
	v_pk_add_f32 v[120:121], v[120:121], v[168:169]
	v_pk_add_f32 v[122:123], v[122:123], v[170:171]
	s_waitcnt vmcnt(0)
	v_pk_add_f32 v[124:125], v[124:125], v[172:173]
	v_pk_add_f32 v[126:127], v[126:127], v[174:175]

; #define PG8_BAR __builtin_amdgcn_s_barrier()
; template <int KK, class Epi, class Sched, bool ALIGN_EPI = true>
; __device__ __forceinline__ void gemm_phase(LAS unsigned char* lds, const bf16* gA, const bf16* gBt, const Sched& S, const Epi& E, const int wid) {
;     ...
;         if constexpr (ALIGN_EPI) { if (wr == 0) PG8_BAR; }
;         E(acc, cur, wr, wc, fr, fq);
;         if (!has_next) break;
.Lp5b_poll2:
	global_load_dword v142, v141, s[20:21] offset:3208 sc1
	s_waitcnt vmcnt(0)
	v_readfirstlane_b32 s69, v142
	s_nop 0
	s_cmp_ge_u32 s69, 16
	s_cbranch_scc1 .Lp5b_go2
	s_sleep 1
	s_branch .Lp5b_poll2
.Lp5b_go2:
	s_add_u32 s72, s70, 0x40000
	s_addc_u32 s73, s71, 0
	global_load_dwordx4 v[200:203], v140, s[72:73] sc0 sc1
	s_add_u32 s72, s72, 0x2000
	s_addc_u32 s73, s73, 0
	global_load_dwordx4 v[204:207], v140, s[72:73] sc0 sc1
	s_add_u32 s72, s72, 0x2000
	s_addc_u32 s73, s73, 0
	global_load_dwordx4 v[208:211], v140, s[72:73] sc0 sc1
	s_add_u32 s72, s72, 0x2000
	s_addc_u32 s73, s73, 0
	global_load_dwordx4 v[212:215], v140, s[72:73] sc0 sc1
	s_add_u32 s72, s72, 0x2000
	s_addc_u32 s73, s73, 0
	global_load_dwordx4 v[216:219], v140, s[72:73] sc0 sc1
	s_add_u32 s72, s72, 0x2000
	s_addc_u32 s73, s73, 0
	global_load_dwordx4 v[220:223], v140, s[72:73] sc0 sc1
	s_add_u32 s72, s72, 0x2000
	s_addc_u32 s73, s73, 0
	global_load_dwordx4 v[224:227], v140, s[72:73] sc0 sc1
	s_add_u32 s72, s72, 0x2000
	s_addc_u32 s73, s73, 0
	global_load_dwordx4 v[228:231], v140, s[72:73] sc0 sc1
	s_add_u32 s72, s72, 0x2000
	s_addc_u32 s73, s73, 0
	global_load_dwordx4 v[232:235], v140, s[72:73] sc0 sc1
	s_add_u32 s72, s72, 0x2000
	s_addc_u32 s73, s73, 0
	global_load_dwordx4 v[236:239], v140, s[72:73] sc0 sc1
	s_add_u32 s72, s72, 0x2000
	s_addc_u32 s73, s73, 0
	global_load_dwordx4 v[240:243], v140, s[72:73] sc0 sc1
	s_add_u32 s72, s72, 0x2000
	s_addc_u32 s73, s73, 0
	global_load_dwordx4 v[244:247], v140, s[72:73] sc0 sc1
	s_add_u32 s72, s72, 0x2000
	s_addc_u32 s73, s73, 0
	global_load_dwordx4 v[160:163], v140, s[72:73] sc0 sc1
	s_add_u32 s72, s72, 0x2000
	s_addc_u32 s73, s73, 0
	global_load_dwordx4 v[164:167], v140, s[72:73] sc0 sc1
	s_add_u32 s72, s72, 0x2000
	s_addc_u32 s73, s73, 0
	global_load_dwordx4 v[168:171], v140, s[72:73] sc0 sc1
	s_add_u32 s72, s72, 0x2000
	s_addc_u32 s73, s73, 0
	global_load_dwordx4 v[172:175], v140, s[72:73] sc0 sc1
	s_waitcnt vmcnt(15)
	v_pk_add_f32 v[0:1], v[0:1], v[200:201]
	v_pk_add_f32 v[2:3], v[2:3], v[202:203]
	s_add_u32 s72, s72, 0x2000
	s_addc_u32 s73, s73, 0
	global_load_dwordx4 v[200:203], v140, s[72:73] sc0 sc1
	s_waitcnt vmcnt(15)
	v_pk_add_f32 v[4:5], v[4:5], v[204:205]
	v_pk_add_f32 v[6:7], v[6:7], v[206:207]
	s_add_u32 s72, s72, 0x2000
	s_addc_u32 s73, s73, 0
	global_load_dwordx4 v[204:207], v140, s[72:73] sc0 sc1
	s_waitcnt vmcnt(15)
	v_pk_add_f32 v[8:9], v[8:9], v[208:209]
	v_pk_add_f32 v[10:11], v[10:11], v[210:211]
	s_add_u32 s72, s72, 0x2000
	s_addc_u32 s73, s73, 0
	global_load_dwordx4 v[208:211], v140, s[72:73] sc0 sc1
	s_waitcnt vmcnt(15)
	v_pk_add_f32 v[12:13], v[12:13], v[212:213]
	v_pk_add_f32 v[14:15], v[14:15], v[214:215]
	s_add_u32 s72, s72, 0x2000
	s_addc_u32 s73, s73, 0
	global_load_dwordx4 v[212:215], v140, s[72:73] sc0 sc1
	s_waitcnt vmcnt(15)
	v_pk_add_f32 v[16:17], v[16:17], v[216:217]
	v_pk_add_f32 v[18:19], v[18:19], v[218:219]
	s_add_u32 s72, s72, 0x2000
	s_addc_u32 s73, s73, 0
	global_load_dwordx4 v[216:219], v140, s[72:73] sc0 sc1
	s_waitcnt vmcnt(15)
	v_pk_add_f32 v[20:21], v[20:21], v[220:221]
	v_pk_add_f32 v[22:23], v[22:23], v[222:223]
	s_add_u32 s72, s72, 0x2000
	s_addc_u32 s73, s73, 0
	global_load_dwordx4 v[220:223], v140, s[72:73] sc0 sc1
	s_waitcnt vmcnt(15)
	v_pk_add_f32 v[24:25], v[24:25], v[224:225]
	v_pk_add_f32 v[26:27], v[26:27], v[226:227]
	s_add_u32 s72, s72, 0x2000
	s_addc_u32 s73, s73, 0
	global_load_dwordx4 v[224:227], v140, s[72:73] sc0 sc1
	s_waitcnt vmcnt(15)
	v_pk_add_f32 v[28:29], v[28:29], v[228:229]
	v_pk_add_f32 v[30:31], v[30:31], v[230:231]
	s_add_u32 s72, s72, 0x2000
	s_addc_u32 s73, s73, 0
	global_load_dwordx4 v[228:231], v140, s[72:73] sc0 sc1
	s_waitcnt vmcnt(15)
	v_pk_add_f32 v[32:33], v[32:33], v[232:233]
	v_pk_add_f32 v[34:35], v[34:35], v[234:235]
	s_add_u32 s72, s72, 0x2000
	s_addc_u32 s73, s73, 0
	global_load_dwordx4 v[232:235], v140, s[72:73] sc0 sc1
	s_waitcnt vmcnt(15)
	v_pk_add_f32 v[36:37], v[36:37], v[236:237]
	v_pk_add_f32 v[38:39], v[38:39], v[238:239]
	s_add_u32 s72, s72, 0x2000
	s_addc_u32 s73, s73, 0
	global_load_dwordx4 v[236:239], v140, s[72:73] sc0 sc1
	s_waitcnt vmcnt(15)
	v_pk_add_f32 v[40:41], v[40:41], v[240:241]
	v_pk_add_f32 v[42:43], v[42:43], v[242:243]
	s_add_u32 s72, s72, 0x2000
	s_addc_u32 s73, s73, 0
	global_load_dwordx4 v[240:243], v140, s[72:73] sc0 sc1
	s_waitcnt vmcnt(15)
	v_pk_add_f32 v[44:45], v[44:45], v[244:245]
	v_pk_add_f32 v[46:47], v[46:47], v[246:247]
	s_add_u32 s72, s72, 0x2000
	s_addc_u32 s73, s73, 0
	global_load_dwordx4 v[244:247], v140, s[72:73] sc0 sc1
	s_waitcnt vmcnt(15)
	v_pk_add_f32 v[48:49], v[48:49], v[160:161]
	v_pk_add_f32 v[50:51], v[50:51], v[162:163]
	s_add_u32 s72, s72, 0x2000
	s_addc_u32 s73, s73, 0
	global_load_dwordx4 v[160:163], v140, s[72:73] sc0 sc1
	s_waitcnt vmcnt(15)
	v_pk_add_f32 v[52:53], v[52:53], v[164:165]
	v_pk_add_f32 v[54:55], v[54:55], v[166:167]
	s_add_u32 s72, s72, 0x2000
	s_addc_u32 s73, s73, 0
	global_load_dwordx4 v[164:167], v140, s[72:73] sc0 sc1
	s_waitcnt vmcnt(15)
	v_pk_add_f32 v[56:57], v[56:57], v[168:169]
	v_pk_add_f32 v[58:59], v[58:59], v[170:171]
	s_add_u32 s72, s72, 0x2000
	s_addc_u32 s73, s73, 0
	global_load_dwordx4 v[168:171], v140, s[72:73] sc0 sc1
	s_waitcnt vmcnt(15)
	v_pk_add_f32 v[60:61], v[60:61], v[172:173]
	v_pk_add_f32 v[62:63], v[62:63], v[174:175]
	s_add_u32 s72, s72, 0x2000
	s_addc_u32 s73, s73, 0
	global_load_dwordx4 v[172:175], v140, s[72:73] sc0 sc1
	s_waitcnt vmcnt(15)
	v_pk_add_f32 v[64:65], v[64:65], v[200:201]
	v_pk_add_f32 v[66:67], v[66:67], v[202:203]
; #define PG8_BAR __builtin_amdgcn_s_barrier()
; template <int KK, class Epi, class Sched, bool ALIGN_EPI = true>
; __device__ __forceinline__ void gemm_phase(LAS unsigned char* lds, const bf16* gA, const bf16* gBt, const Sched& S, const Epi& E, const int wid) {
;     ...
;         if constexpr (ALIGN_EPI) { if (wr == 0) PG8_BAR; }
;         E(acc, cur, wr, wc, fr, fq);
;         if (!has_next) break;
.Lp5b_poll3:
	global_load_dword v142, v141, s[20:21] offset:3212 sc1
	s_waitcnt vmcnt(0)
	v_readfirstlane_b32 s69, v142
	s_nop 0
	s_cmp_ge_u32 s69, 16
	s_cbranch_scc1 .Lp5b_go3
	s_sleep 1
	s_branch .Lp5b_poll3
.Lp5b_go3:
	s_add_u32 s72, s70, 0x80000
	s_addc_u32 s73, s71, 0
	global_load_dwordx4 v[200:203], v140, s[72:73] sc0 sc1
	s_waitcnt vmcnt(15)
	v_pk_add_f32 v[68:69], v[68:69], v[204:205]
	v_pk_add_f32 v[70:71], v[70:71], v[206:207]
	s_add_u32 s72, s72, 0x2000
	s_addc_u32 s73, s73, 0
	global_load_dwordx4 v[204:207], v140, s[72:73] sc0 sc1
	s_waitcnt vmcnt(15)
	v_pk_add_f32 v[72:73], v[72:73], v[208:209]
	v_pk_add_f32 v[74:75], v[74:75], v[210:211]
	s_add_u32 s72, s72, 0x2000
	s_addc_u32 s73, s73, 0
	global_load_dwordx4 v[208:211], v140, s[72:73] sc0 sc1
	s_waitcnt vmcnt(15)
	v_pk_add_f32 v[76:77], v[76:77], v[212:213]
	v_pk_add_f32 v[78:79], v[78:79], v[214:215]
	s_add_u32 s72, s72, 0x2000
	s_addc_u32 s73, s73, 0
	global_load_dwordx4 v[212:215], v140, s[72:73] sc0 sc1
	s_waitcnt vmcnt(15)
	v_pk_add_f32 v[80:81], v[80:81], v[216:217]
	v_pk_add_f32 v[82:83], v[82:83], v[218:219]
	s_add_u32 s72, s72, 0x2000
	s_addc_u32 s73, s73, 0
	global_load_dwordx4 v[216:219], v140, s[72:73] sc0 sc1
	s_waitcnt vmcnt(15)
	v_pk_add_f32 v[84:85], v[84:85], v[220:221]
	v_pk_add_f32 v[86:87], v[86:87], v[222:223]
	s_add_u32 s72, s72, 0x2000
	s_addc_u32 s73, s73, 0
	global_load_dwordx4 v[220:223], v140, s[72:73] sc0 sc1
	s_waitcnt vmcnt(15)
	v_pk_add_f32 v[88:89], v[88:89], v[224:225]
	v_pk_add_f32 v[90:91], v[90:91], v[226:227]
	s_add_u32 s72, s72, 0x2000
	s_addc_u32 s73, s73, 0
	global_load_dwordx4 v[224:227], v140, s[72:73] sc0 sc1
	s_waitcnt vmcnt(15)
	v_pk_add_f32 v[92:93], v[92:93], v[228:229]
	v_pk_add_f32 v[94:95], v[94:95], v[230:231]
	s_add_u32 s72, s72, 0x2000
	s_addc_u32 s73, s73, 0
	global_load_dwordx4 v[228:231], v140, s[72:73] sc0 sc1
	s_waitcnt vmcnt(15)
	v_pk_add_f32 v[96:97], v[96:97], v[232:233]
	v_pk_add_f32 v[98:99], v[98:99], v[234:235]
	s_add_u32 s72, s72, 0x2000
	s_addc_u32 s73, s73, 0
	global_load_dwordx4 v[232:235], v140, s[72:73] sc0 sc1
	s_waitcnt vmcnt(15)
	v_pk_add_f32 v[100:101], v[100:101], v[236:237]
	v_pk_add_f32 v[102:103], v[102:103], v[238:239]
	s_add_u32 s72, s72, 0x2000
	s_addc_u32 s73, s73, 0
	global_load_dwordx4 v[236:239], v140, s[72:73] sc0 sc1
	s_waitcnt vmcnt(15)
	v_pk_add_f32 v[104:105], v[104:105], v[240:241]
	v_pk_add_f32 v[106:107], v[106:107], v[242:243]
	s_add_u32 s72, s72, 0x2000
	s_addc_u32 s73, s73, 0
	global_load_dwordx4 v[240:243], v140, s[72:73] sc0 sc1
	s_waitcnt vmcnt(15)
	v_pk_add_f32 v[108:109], v[108:109], v[244:245]
	v_pk_add_f32 v[110:111], v[110:111], v[246:247]
	s_add_u32 s72, s72, 0x2000
	s_addc_u32 s73, s73, 0
	global_load_dwordx4 v[244:247], v140, s[72:73] sc0 sc1
	s_waitcnt vmcnt(15)
	v_pk_add_f32 v[112:113], v[112:113], v[160:161]
	v_pk_add_f32 v[114:115], v[114:115], v[162:163]
	s_add_u32 s72, s72, 0x2000
	s_addc_u32 s73, s73, 0
	global_load_dwordx4 v[160:163], v140, s[72:73] sc0 sc1
	s_waitcnt vmcnt(15)
	v_pk_add_f32 v[116:117], v[116:117], v[164:165]
	v_pk_add_f32 v[118:119], v[118:119], v[166:167]
	s_add_u32 s72, s72, 0x2000
	s_addc_u32 s73, s73, 0
	global_load_dwordx4 v[164:167], v140, s[72:73] sc0 sc1
	s_waitcnt vmcnt(15)
	v_pk_add_f32 v[120:121], v[120:121], v[168:169]
	v_pk_add_f32 v[122:123], v[122:123], v[170:171]
	s_add_u32 s72, s72, 0x2000
	s_addc_u32 s73, s73, 0
	global_load_dwordx4 v[168:171], v140, s[72:73] sc0 sc1
	s_waitcnt vmcnt(15)
	v_pk_add_f32 v[124:125], v[124:125], v[172:173]
	v_pk_add_f32 v[126:127], v[126:127], v[174:175]
	s_add_u32 s72, s72, 0x2000
	s_addc_u32 s73, s73, 0
	global_load_dwordx4 v[172:175], v140, s[72:73] sc0 sc1
	s_waitcnt vmcnt(15)
; #define PG8_BAR __builtin_amdgcn_s_barrier()
; template <int KK, class Epi, class Sched, bool ALIGN_EPI = true>
; __device__ __forceinline__ void gemm_phase(LAS unsigned char* lds, const bf16* gA, const bf16* gBt, const Sched& S, const Epi& E, const int wid) {
;     ...
;         if constexpr (ALIGN_EPI) { if (wr == 0) PG8_BAR; }
;         E(acc, cur, wr, wc, fr, fq);
;         if (!has_next) break;
	v_pk_add_f32 v[0:1], v[0:1], v[200:201]
	v_pk_add_f32 v[2:3], v[2:3], v[202:203]
	s_add_u32 s72, s72, 0x2000
	s_addc_u32 s73, s73, 0
	global_load_dwordx4 v[200:203], v140, s[72:73] sc0 sc1
	s_waitcnt vmcnt(15)
	v_pk_add_f32 v[4:5], v[4:5], v[204:205]
	v_pk_add_f32 v[6:7], v[6:7], v[206:207]
	s_add_u32 s72, s72, 0x2000
	s_addc_u32 s73, s73, 0
	global_load_dwordx4 v[204:207], v140, s[72:73] sc0 sc1
	s_waitcnt vmcnt(15)
	v_pk_add_f32 v[8:9], v[8:9], v[208:209]
	v_pk_add_f32 v[10:11], v[10:11], v[210:211]
	s_add_u32 s72, s72, 0x2000
	s_addc_u32 s73, s73, 0
	global_load_dwordx4 v[208:211], v140, s[72:73] sc0 sc1
	s_waitcnt vmcnt(15)
	v_pk_add_f32 v[12:13], v[12:13], v[212:213]
	v_pk_add_f32 v[14:15], v[14:15], v[214:215]
	s_add_u32 s72, s72, 0x2000
	s_addc_u32 s73, s73, 0
	global_load_dwordx4 v[212:215], v140, s[72:73] sc0 sc1
	s_waitcnt vmcnt(15)
	v_pk_add_f32 v[16:17], v[16:17], v[216:217]
	v_pk_add_f32 v[18:19], v[18:19], v[218:219]
	s_add_u32 s72, s72, 0x2000
	s_addc_u32 s73, s73, 0
	global_load_dwordx4 v[216:219], v140, s[72:73] sc0 sc1
	s_waitcnt vmcnt(15)
	v_pk_add_f32 v[20:21], v[20:21], v[220:221]
	v_pk_add_f32 v[22:23], v[22:23], v[222:223]
	s_add_u32 s72, s72, 0x2000
	s_addc_u32 s73, s73, 0
	global_load_dwordx4 v[220:223], v140, s[72:73] sc0 sc1
	s_waitcnt vmcnt(15)
	v_pk_add_f32 v[24:25], v[24:25], v[224:225]
	v_pk_add_f32 v[26:27], v[26:27], v[226:227]
	s_add_u32 s72, s72, 0x2000
	s_addc_u32 s73, s73, 0
	global_load_dwordx4 v[224:227], v140, s[72:73] sc0 sc1
	s_waitcnt vmcnt(15)
	v_pk_add_f32 v[28:29], v[28:29], v[228:229]
	v_pk_add_f32 v[30:31], v[30:31], v[230:231]
	s_add_u32 s72, s72, 0x2000
	s_addc_u32 s73, s73, 0
	global_load_dwordx4 v[228:231], v140, s[72:73] sc0 sc1
	s_waitcnt vmcnt(15)
	v_pk_add_f32 v[32:33], v[32:33], v[232:233]
	v_pk_add_f32 v[34:35], v[34:35], v[234:235]
	s_add_u32 s72, s72, 0x2000
	s_addc_u32 s73, s73, 0
	global_load_dwordx4 v[232:235], v140, s[72:73] sc0 sc1
	s_waitcnt vmcnt(15)
	v_pk_add_f32 v[36:37], v[36:37], v[236:237]
	v_pk_add_f32 v[38:39], v[38:39], v[238:239]
	s_add_u32 s72, s72, 0x2000
	s_addc_u32 s73, s73, 0
	global_load_dwordx4 v[236:239], v140, s[72:73] sc0 sc1
	s_waitcnt vmcnt(15)
	v_pk_add_f32 v[40:41], v[40:41], v[240:241]
	v_pk_add_f32 v[42:43], v[42:43], v[242:243]
	s_add_u32 s72, s72, 0x2000
	s_addc_u32 s73, s73, 0
	global_load_dwordx4 v[240:243], v140, s[72:73] sc0 sc1
	s_waitcnt vmcnt(15)
	v_pk_add_f32 v[44:45], v[44:45], v[244:245]
	v_pk_add_f32 v[46:47], v[46:47], v[246:247]
	s_add_u32 s72, s72, 0x2000
	s_addc_u32 s73, s73, 0
	global_load_dwordx4 v[244:247], v140, s[72:73] sc0 sc1
	s_waitcnt vmcnt(15)
	v_pk_add_f32 v[48:49], v[48:49], v[160:161]
	v_pk_add_f32 v[50:51], v[50:51], v[162:163]
	s_add_u32 s72, s72, 0x2000
	s_addc_u32 s73, s73, 0
	global_load_dwordx4 v[160:163], v140, s[72:73] sc0 sc1
	s_waitcnt vmcnt(15)
	v_pk_add_f32 v[52:53], v[52:53], v[164:165]
	v_pk_add_f32 v[54:55], v[54:55], v[166:167]
	s_add_u32 s72, s72, 0x2000
	s_addc_u32 s73, s73, 0
	global_load_dwordx4 v[164:167], v140, s[72:73] sc0 sc1
	s_waitcnt vmcnt(15)
	v_pk_add_f32 v[56:57], v[56:57], v[168:169]
	v_pk_add_f32 v[58:59], v[58:59], v[170:171]
	s_add_u32 s72, s72, 0x2000
	s_addc_u32 s73, s73, 0
	global_load_dwordx4 v[168:171], v140, s[72:73] sc0 sc1
	s_waitcnt vmcnt(15)
	v_pk_add_f32 v[60:61], v[60:61], v[172:173]
	v_pk_add_f32 v[62:63], v[62:63], v[174:175]
	s_add_u32 s72, s72, 0x2000
	s_addc_u32 s73, s73, 0
	global_load_dwordx4 v[172:175], v140, s[72:73] sc0 sc1
	s_waitcnt vmcnt(15)
	v_pk_add_f32 v[64:65], v[64:65], v[200:201]
	v_pk_add_f32 v[66:67], v[66:67], v[202:203]

; #define PG8_BAR __builtin_amdgcn_s_barrier()
; template <int KK, class Epi, class Sched, bool ALIGN_EPI = true>
; __device__ __forceinline__ void gemm_phase(LAS unsigned char* lds, const bf16* gA, const bf16* gBt, const Sched& S, const Epi& E, const int wid) {
;     ...
;         if constexpr (ALIGN_EPI) { if (wr == 0) PG8_BAR; }
;         E(acc, cur, wr, wc, fr, fq);
;         if (!has_next) break;
.Lp5b_go1:
	s_add_u32 s72, s70, 0x0
	s_addc_u32 s73, s71, 0
	global_load_dwordx4 v[200:203], v140, s[72:73] sc0 sc1
	s_waitcnt vmcnt(15)
	v_pk_add_f32 v[68:69], v[68:69], v[204:205]
	v_pk_add_f32 v[70:71], v[70:71], v[206:207]
	s_add_u32 s72, s72, 0x2000
	s_addc_u32 s73, s73, 0
	global_load_dwordx4 v[204:207], v140, s[72:73] sc0 sc1
	s_waitcnt vmcnt(15)
	v_pk_add_f32 v[72:73], v[72:73], v[208:209]
	v_pk_add_f32 v[74:75], v[74:75], v[210:211]
	s_add_u32 s72, s72, 0x2000
	s_addc_u32 s73, s73, 0
	global_load_dwordx4 v[208:211], v140, s[72:73] sc0 sc1
	s_waitcnt vmcnt(15)
	v_pk_add_f32 v[76:77], v[76:77], v[212:213]
	v_pk_add_f32 v[78:79], v[78:79], v[214:215]
	s_add_u32 s72, s72, 0x2000
	s_addc_u32 s73, s73, 0
	global_load_dwordx4 v[212:215], v140, s[72:73] sc0 sc1
	s_waitcnt vmcnt(15)
	v_pk_add_f32 v[80:81], v[80:81], v[216:217]
	v_pk_add_f32 v[82:83], v[82:83], v[218:219]
	s_add_u32 s72, s72, 0x2000
	s_addc_u32 s73, s73, 0
	global_load_dwordx4 v[216:219], v140, s[72:73] sc0 sc1
	s_waitcnt vmcnt(15)
	v_pk_add_f32 v[84:85], v[84:85], v[220:221]
	v_pk_add_f32 v[86:87], v[86:87], v[222:223]
	s_add_u32 s72, s72, 0x2000
	s_addc_u32 s73, s73, 0
	global_load_dwordx4 v[220:223], v140, s[72:73] sc0 sc1
	s_waitcnt vmcnt(15)
	v_pk_add_f32 v[88:89], v[88:89], v[224:225]
	v_pk_add_f32 v[90:91], v[90:91], v[226:227]
	s_add_u32 s72, s72, 0x2000
	s_addc_u32 s73, s73, 0
	global_load_dwordx4 v[224:227], v140, s[72:73] sc0 sc1
	s_waitcnt vmcnt(15)
	v_pk_add_f32 v[92:93], v[92:93], v[228:229]
	v_pk_add_f32 v[94:95], v[94:95], v[230:231]
	s_add_u32 s72, s72, 0x2000
	s_addc_u32 s73, s73, 0
	global_load_dwordx4 v[228:231], v140, s[72:73] sc0 sc1
	s_waitcnt vmcnt(15)
	v_pk_add_f32 v[96:97], v[96:97], v[232:233]
	v_pk_add_f32 v[98:99], v[98:99], v[234:235]
	s_add_u32 s72, s72, 0x2000
	s_addc_u32 s73, s73, 0
	global_load_dwordx4 v[232:235], v140, s[72:73] sc0 sc1
	s_waitcnt vmcnt(15)
	v_pk_add_f32 v[100:101], v[100:101], v[236:237]
	v_pk_add_f32 v[102:103], v[102:103], v[238:239]
	s_add_u32 s72, s72, 0x2000
	s_addc_u32 s73, s73, 0
	global_load_dwordx4 v[236:239], v140, s[72:73] sc0 sc1
	s_waitcnt vmcnt(15)
	v_pk_add_f32 v[104:105], v[104:105], v[240:241]
	v_pk_add_f32 v[106:107], v[106:107], v[242:243]
	s_add_u32 s72, s72, 0x2000
	s_addc_u32 s73, s73, 0
	global_load_dwordx4 v[240:243], v140, s[72:73] sc0 sc1
	s_waitcnt vmcnt(15)
	v_pk_add_f32 v[108:109], v[108:109], v[244:245]
	v_pk_add_f32 v[110:111], v[110:111], v[246:247]
	s_add_u32 s72, s72, 0x2000
	s_addc_u32 s73, s73, 0
	global_load_dwordx4 v[244:247], v140, s[72:73] sc0 sc1
	s_waitcnt vmcnt(15)
	v_pk_add_f32 v[112:113], v[112:113], v[160:161]
	v_pk_add_f32 v[114:115], v[114:115], v[162:163]
	s_add_u32 s72, s72, 0x2000
	s_addc_u32 s73, s73, 0
	global_load_dwordx4 v[160:163], v140, s[72:73] sc0 sc1
	s_waitcnt vmcnt(15)
	v_pk_add_f32 v[116:117], v[116:117], v[164:165]
	v_pk_add_f32 v[118:119], v[118:119], v[166:167]
	s_add_u32 s72, s72, 0x2000
	s_addc_u32 s73, s73, 0
	global_load_dwordx4 v[164:167], v140, s[72:73] sc0 sc1
	s_waitcnt vmcnt(15)
	v_pk_add_f32 v[120:121], v[120:121], v[168:169]
	v_pk_add_f32 v[122:123], v[122:123], v[170:171]
	s_add_u32 s72, s72, 0x2000
	s_addc_u32 s73, s73, 0
	global_load_dwordx4 v[168:171], v140, s[72:73] sc0 sc1
	s_waitcnt vmcnt(15)
	v_pk_add_f32 v[124:125], v[124:125], v[172:173]
	v_pk_add_f32 v[126:127], v[126:127], v[174:175]
	s_add_u32 s72, s72, 0x2000
	s_addc_u32 s73, s73, 0
	global_load_dwordx4 v[172:175], v140, s[72:73] sc0 sc1
	s_waitcnt vmcnt(15)
	v_pk_add_f32 v[0:1], v[0:1], v[200:201]
	v_pk_add_f32 v[2:3], v[2:3], v[202:203]
	s_add_u32 s72, s72, 0x2000
	s_addc_u32 s73, s73, 0
	global_load_dwordx4 v[200:203], v140, s[72:73] sc0 sc1
	s_waitcnt vmcnt(15)
	v_pk_add_f32 v[4:5], v[4:5], v[204:205]
	v_pk_add_f32 v[6:7], v[6:7], v[206:207]
	s_add_u32 s72, s72, 0x2000
	s_addc_u32 s73, s73, 0
	global_load_dwordx4 v[204:207], v140, s[72:73] sc0 sc1
	s_waitcnt vmcnt(15)
	v_pk_add_f32 v[8:9], v[8:9], v[208:209]
	v_pk_add_f32 v[10:11], v[10:11], v[210:211]
	s_add_u32 s72, s72, 0x2000
	s_addc_u32 s73, s73, 0
	global_load_dwordx4 v[208:211], v140, s[72:73] sc0 sc1
	s_waitcnt vmcnt(15)
	v_pk_add_f32 v[12:13], v[12:13], v[212:213]
	v_pk_add_f32 v[14:15], v[14:15], v[214:215]
	s_add_u32 s72, s72, 0x2000
	s_addc_u32 s73, s73, 0
	global_load_dwordx4 v[212:215], v140, s[72:73] sc0 sc1
	s_waitcnt vmcnt(15)
; #define PG8_BAR __builtin_amdgcn_s_barrier()
; template <int KK, class Epi, class Sched, bool ALIGN_EPI = true>
; __device__ __forceinline__ void gemm_phase(LAS unsigned char* lds, const bf16* gA, const bf16* gBt, const Sched& S, const Epi& E, const int wid) {
;     ...
;         if constexpr (ALIGN_EPI) { if (wr == 0) PG8_BAR; }
;         E(acc, cur, wr, wc, fr, fq);
;         if (!has_next) break;
	v_pk_add_f32 v[16:17], v[16:17], v[216:217]
	v_pk_add_f32 v[18:19], v[18:19], v[218:219]
	s_add_u32 s72, s72, 0x2000
	s_addc_u32 s73, s73, 0
	global_load_dwordx4 v[216:219], v140, s[72:73] sc0 sc1
	s_waitcnt vmcnt(15)
	v_pk_add_f32 v[20:21], v[20:21], v[220:221]
	v_pk_add_f32 v[22:23], v[22:23], v[222:223]
	s_add_u32 s72, s72, 0x2000
	s_addc_u32 s73, s73, 0
	global_load_dwordx4 v[220:223], v140, s[72:73] sc0 sc1
	s_waitcnt vmcnt(15)
	v_pk_add_f32 v[24:25], v[24:25], v[224:225]
	v_pk_add_f32 v[26:27], v[26:27], v[226:227]
	s_add_u32 s72, s72, 0x2000
	s_addc_u32 s73, s73, 0
	global_load_dwordx4 v[224:227], v140, s[72:73] sc0 sc1
	s_waitcnt vmcnt(15)
	v_pk_add_f32 v[28:29], v[28:29], v[228:229]
	v_pk_add_f32 v[30:31], v[30:31], v[230:231]
	s_add_u32 s72, s72, 0x2000
	s_addc_u32 s73, s73, 0
	global_load_dwordx4 v[228:231], v140, s[72:73] sc0 sc1
	s_waitcnt vmcnt(15)
	v_pk_add_f32 v[32:33], v[32:33], v[232:233]
	v_pk_add_f32 v[34:35], v[34:35], v[234:235]
	s_add_u32 s72, s72, 0x2000
	s_addc_u32 s73, s73, 0
	global_load_dwordx4 v[232:235], v140, s[72:73] sc0 sc1
	s_waitcnt vmcnt(15)
	v_pk_add_f32 v[36:37], v[36:37], v[236:237]
	v_pk_add_f32 v[38:39], v[38:39], v[238:239]
	s_add_u32 s72, s72, 0x2000
	s_addc_u32 s73, s73, 0
	global_load_dwordx4 v[236:239], v140, s[72:73] sc0 sc1
	s_waitcnt vmcnt(15)
	v_pk_add_f32 v[40:41], v[40:41], v[240:241]
	v_pk_add_f32 v[42:43], v[42:43], v[242:243]
	s_add_u32 s72, s72, 0x2000
	s_addc_u32 s73, s73, 0
	global_load_dwordx4 v[240:243], v140, s[72:73] sc0 sc1
	s_waitcnt vmcnt(15)
	v_pk_add_f32 v[44:45], v[44:45], v[244:245]
	v_pk_add_f32 v[46:47], v[46:47], v[246:247]
	s_add_u32 s72, s72, 0x2000
	s_addc_u32 s73, s73, 0
	global_load_dwordx4 v[244:247], v140, s[72:73] sc0 sc1
	s_waitcnt vmcnt(15)
	v_pk_add_f32 v[48:49], v[48:49], v[160:161]
	v_pk_add_f32 v[50:51], v[50:51], v[162:163]
	s_add_u32 s72, s72, 0x2000
	s_addc_u32 s73, s73, 0
	global_load_dwordx4 v[160:163], v140, s[72:73] sc0 sc1
	s_waitcnt vmcnt(15)
	v_pk_add_f32 v[52:53], v[52:53], v[164:165]
	v_pk_add_f32 v[54:55], v[54:55], v[166:167]
	s_add_u32 s72, s72, 0x2000
	s_addc_u32 s73, s73, 0
	global_load_dwordx4 v[164:167], v140, s[72:73] sc0 sc1
	s_waitcnt vmcnt(15)
	v_pk_add_f32 v[56:57], v[56:57], v[168:169]
	v_pk_add_f32 v[58:59], v[58:59], v[170:171]
	s_add_u32 s72, s72, 0x2000
	s_addc_u32 s73, s73, 0
	global_load_dwordx4 v[168:171], v140, s[72:73] sc0 sc1
	s_waitcnt vmcnt(15)
	v_pk_add_f32 v[60:61], v[60:61], v[172:173]
	v_pk_add_f32 v[62:63], v[62:63], v[174:175]
	s_add_u32 s72, s72, 0x2000
	s_addc_u32 s73, s73, 0
	global_load_dwordx4 v[172:175], v140, s[72:73] sc0 sc1
	s_waitcnt vmcnt(15)
	v_pk_add_f32 v[64:65], v[64:65], v[200:201]
	v_pk_add_f32 v[66:67], v[66:67], v[202:203]
	s_waitcnt vmcnt(14)
	v_pk_add_f32 v[68:69], v[68:69], v[204:205]
	v_pk_add_f32 v[70:71], v[70:71], v[206:207]
	s_waitcnt vmcnt(13)
	v_pk_add_f32 v[72:73], v[72:73], v[208:209]
	v_pk_add_f32 v[74:75], v[74:75], v[210:211]
	s_waitcnt vmcnt(12)
	v_pk_add_f32 v[76:77], v[76:77], v[212:213]
	v_pk_add_f32 v[78:79], v[78:79], v[214:215]
	s_waitcnt vmcnt(11)
	v_pk_add_f32 v[80:81], v[80:81], v[216:217]
	v_pk_add_f32 v[82:83], v[82:83], v[218:219]
	s_waitcnt vmcnt(10)
	v_pk_add_f32 v[84:85], v[84:85], v[220:221]
	v_pk_add_f32 v[86:87], v[86:87], v[222:223]
	s_waitcnt vmcnt(9)
	v_pk_add_f32 v[88:89], v[88:89], v[224:225]
	v_pk_add_f32 v[90:91], v[90:91], v[226:227]
	s_waitcnt vmcnt(8)
	v_pk_add_f32 v[92:93], v[92:93], v[228:229]
	v_pk_add_f32 v[94:95], v[94:95], v[230:231]
	s_waitcnt vmcnt(7)
	v_pk_add_f32 v[96:97], v[96:97], v[232:233]
	v_pk_add_f32 v[98:99], v[98:99], v[234:235]
	s_waitcnt vmcnt(6)
	v_pk_add_f32 v[100:101], v[100:101], v[236:237]
	v_pk_add_f32 v[102:103], v[102:103], v[238:239]
	s_waitcnt vmcnt(5)
	v_pk_add_f32 v[104:105], v[104:105], v[240:241]
	v_pk_add_f32 v[106:107], v[106:107], v[242:243]
	s_waitcnt vmcnt(4)
	v_pk_add_f32 v[108:109], v[108:109], v[244:245]
	v_pk_add_f32 v[110:111], v[110:111], v[246:247]
	s_waitcnt vmcnt(3)
	v_pk_add_f32 v[112:113], v[112:113], v[160:161]
	v_pk_add_f32 v[114:115], v[114:115], v[162:163]
	s_waitcnt vmcnt(2)
	v_pk_add_f32 v[116:117], v[116:117], v[164:165]
	v_pk_add_f32 v[118:119], v[118:119], v[166:167]
	s_waitcnt vmcnt(1)
	v_pk_add_f32 v[120:121], v[120:121], v[168:169]
	v_pk_add_f32 v[122:123], v[122:123], v[170:171]
	s_waitcnt vmcnt(0)
	v_pk_add_f32 v[124:125], v[124:125], v[172:173]
	v_pk_add_f32 v[126:127], v[126:127], v[174:175]
